# third split-phase barrier: arrive after the input projection, run the p->bf16 / stats-zero step (independent of it), wait, then the rest of P2
# baseline (speedup 1.0000x reference)
; #define LAS __attribute__((address_space(3)))
; __device__ __forceinline__ unsigned xb_ld(unsigned* p)              { return __hip_atomic_load(p, __ATOMIC_RELAXED, __HIP_MEMORY_SCOPE_AGENT); }
; __device__ __forceinline__ unsigned xb_add(unsigned* p, unsigned v) { return __hip_atomic_fetch_add(p, v, __ATOMIC_RELAXED, __HIP_MEMORY_SCOPE_AGENT); }
; __device__ __forceinline__ void xcd_barrier(const XcdBarrier& b) {
;     asm volatile("s_waitcnt vmcnt(0)" ::: "memory");
;     __syncthreads();
;     if (threadIdx.x == 0) {
;         unsigned long long bar_ = (unsigned long long)b.bar; unsigned bx = b.x;
;         asm volatile("" : "+s"(bar_), "+s"(bx));
;         unsigned* bar = (unsigned*)bar_;
;         __builtin_amdgcn_s_waitcnt(0);
;         unsigned nloc = b.st[0], nx = b.st[1];
;         if (nloc == 0u) { xcd_barrier_complete(bar, bx, nloc, nx); b.st[0] = nloc; b.st[1] = nx; }
;         const unsigned old = xb_add(&bar[XB_XSUB(bx)], 1u);
;         const unsigned gen = old / nloc;
;         if (old + 1u == (gen + 1u) * nloc) {
;             __builtin_amdgcn_fence(__ATOMIC_RELEASE, "agent");
;             asm volatile("s_waitcnt vmcnt(0)" ::: "memory");
;             const unsigned og = xb_add(&bar[XB_TOP], 1u);
;             const unsigned tg = og / nx;
;             if (og + 1u == (tg + 1u) * nx) xb_add(&bar[XB_TOPGEN], 1u);
;             else XB_SPIN(xb_ld(&bar[XB_TOPGEN]) == tg, bar);
;             __builtin_amdgcn_fence(__ATOMIC_ACQUIRE, "agent");
;             xb_add(&bar[XB_XGEN(bx)], 1u);
;             asm volatile("s_waitcnt vmcnt(0)" ::: "memory");
;         } else {
;             XB_SPIN(xb_ld(&bar[XB_XGEN(bx)]) == gen, bar);
;             __builtin_amdgcn_fence(__ATOMIC_ACQUIRE, "agent");
;             asm volatile("s_waitcnt vmcnt(0)" ::: "memory");
;         }
;     }
;     __syncthreads();
; __global__ void __launch_bounds__(512, 2) fwd_megakernel(Params p_) {
;     ...
;         if (PHM & 8)
;         {
;             TID_VARS
;             KARGS
;             { LAS float* WD0 = (LAS float*)lds; const float* wdw = p->in[I_WDW] + (size_t)l * 31 * 512;
;               for (int e = tid; e < 31 * 512; e += 512) WD0[e] = wdw[e]; }
.LBB0_247:
	s_waitcnt vmcnt(0)
	s_waitcnt vmcnt(0) lgkmcnt(0)
	s_barrier
	s_mov_b64 s[38:39], exec
	v_readlane_b32 s2, v253, 5
	v_readlane_b32 s3, v253, 6
	s_and_b64 s[2:3], s[38:39], s[2:3]
	s_mov_b64 exec, s[2:3]
	s_cbranch_execz .LBB0_291
	s_add_i32 s98, s98, 1
	v_mov_b32_e32 v0, 0x20fa0
	ds_read_b64 v[2:3], v0
	v_readlane_b32 s10, v253, 2
	v_readlane_b32 s11, v253, 3
	v_readlane_b32 s12, v253, 4
	s_lshl_b32 s12, s12, 6
	s_add_i32 s12, s12, 0x3600
	s_add_u32 s14, s10, s12
	s_addc_u32 s15, s11, 0
	s_add_u32 s10, s10, 0x3b00
	s_addc_u32 s11, s11, 0
	v_mov_b64_e32 v[4:5], s[14:15]
	v_mov_b32_e32 v8, 1
	flat_atomic_add v6, v[4:5], v8 sc0
	s_waitcnt vmcnt(0) lgkmcnt(0)
	v_readfirstlane_b32 s12, v6
	v_readfirstlane_b32 s13, v2
	s_mul_i32 s13, s13, s98
	s_add_i32 s12, s12, 1
	s_cmp_lg_u32 s12, s13
	s_cbranch_scc1 .Lgb_done_2
	v_mov_b64_e32 v[4:5], s[10:11]
	buffer_wbl2 sc1
	s_waitcnt vmcnt(0) lgkmcnt(0)
	flat_atomic_add v7, v[4:5], v8 sc0
	s_waitcnt vmcnt(0) lgkmcnt(0)
.Lgb_done_2:
.LBB0_291:
	s_or_b64 exec, exec, s[38:39]
	v_readlane_b32 s0, v253, 0
	v_mov_b32_e32 v48, v246
	v_readlane_b32 s1, v253, 1
	s_waitcnt lgkmcnt(0)
	s_barrier
	s_mov_b32 s100, 0
	v_readlane_b32 s101, v253, 7
	s_nop 0
	s_bfe_u32 s101, s101, 0x10003
.Lp2_hd:
	s_movk_i32 s2, 0x3e00
	v_writelane_b32 v255, s0, 10
	s_load_dwordx2 s[6:7], s[0:1], 0xd0
	v_ashrrev_i32_e32 v49, 31, v48
	v_writelane_b32 v255, s1, 11
	s_cmp_eq_u32 s100, 2
	s_cbranch_scc1 .Lp2_go
	s_mov_b32 s100, 1
	s_waitcnt lgkmcnt(0)
	s_branch .LBB0_504
.Lp2_go:
	v_readfirstlane_b32 s0, v48
	v_cmp_gt_i32_e32 vcc, s2, v48
	s_nop 0
	v_writelane_b32 v255, s0, 12
	s_and_saveexec_b64 s[8:9], vcc
	s_cbranch_execz .LBB0_306
	v_readlane_b32 s0, v255, 10
	v_readlane_b32 s1, v255, 11
	s_load_dwordx2 s[10:11], s[0:1], 0x68
	v_max_i32_e32 v0, 0x3c00, v48
	v_sub_u32_e32 v0, v0, v48
	v_add_u32_e32 v1, 0x1ff, v0
	s_movk_i32 s2, 0x1ff
	v_cmp_lt_u32_e32 vcc, s2, v1
	s_mov_b64 s[4:5], -1
	v_mov_b32_e32 v0, v48
	v_mov_b64_e32 v[2:3], v[48:49]
	s_and_saveexec_b64 s[12:13], vcc
	s_cbranch_execz .LBB0_303
	v_lshrrev_b32_e32 v2, 9, v1
	v_readlane_b32 s0, v255, 6
	s_mul_i32 s3, s0, 0xf800
	v_add_u32_e32 v4, -1, v2
	s_mul_hi_u32 s2, s0, 0xf800
	s_waitcnt lgkmcnt(0)
	s_add_u32 s14, s10, s3
	v_lshrrev_b32_e32 v3, 1, v4
	s_addc_u32 s15, s11, s2
	v_add_u32_e32 v1, 0x200, v48
	v_mov_b32_e32 v0, v48
	v_add_u32_e32 v3, 1, v3
	v_cmp_lt_u32_e32 vcc, 13, v4
	v_mov_b32_e32 v6, 0
	v_readlane_b32 s1, v255, 7
	s_and_saveexec_b64 s[16:17], vcc
	s_cbranch_execz .LBB0_297
	v_and_b32_e32 v4, -8, v3
	v_lshl_add_u32 v5, v48, 2, 0
	s_mov_b32 s2, 0
	s_mov_b64 s[18:19], 0

; __global__ void __launch_bounds__(512, 2) fwd_megakernel(Params p_) {
;     ...
;             {
;                 for (size_t e = gt; e < (size_t)M_TOK * 2; e += NGT) STATS[e] = 0.f;
.LBB0_504:
	s_cmp_eq_u32 s100, 2
	s_cbranch_scc0 .Lp2_504c
	s_mov_b32 s100, 0
	s_branch .LBB0_514

; __device__ __forceinline__ unsigned xb_ld(unsigned* p)              { return __hip_atomic_load(p, __ATOMIC_RELAXED, __HIP_MEMORY_SCOPE_AGENT); }
; __device__ __forceinline__ unsigned xb_add(unsigned* p, unsigned v) { return __hip_atomic_fetch_add(p, v, __ATOMIC_RELAXED, __HIP_MEMORY_SCOPE_AGENT); }
; #define XB_SPIN(cond, bar) do { unsigned _sp = 0; while (cond) { __builtin_amdgcn_s_sleep(1); \
;     if ((++_sp & 255u) == 0u) { if (xb_ld(&(bar)[XB_TMO])) break; if (_sp > XB_SPIN_CAP) { atomicAdd(&(bar)[XB_TMO], 1u); break; } } } } while (0)
; __device__ __forceinline__ void xcd_barrier(const XcdBarrier& b) {
;     asm volatile("s_waitcnt vmcnt(0)" ::: "memory");
;     __syncthreads();
;     if (threadIdx.x == 0) {
;         unsigned long long bar_ = (unsigned long long)b.bar; unsigned bx = b.x;
;         asm volatile("" : "+s"(bar_), "+s"(bx));
;         unsigned* bar = (unsigned*)bar_;
;         __builtin_amdgcn_s_waitcnt(0);
;         unsigned nloc = b.st[0], nx = b.st[1];
;         if (nloc == 0u) { xcd_barrier_complete(bar, bx, nloc, nx); b.st[0] = nloc; b.st[1] = nx; }
;         const unsigned old = xb_add(&bar[XB_XSUB(bx)], 1u);
;         const unsigned gen = old / nloc;
;         if (old + 1u == (gen + 1u) * nloc) {
;             __builtin_amdgcn_fence(__ATOMIC_RELEASE, "agent");
;             asm volatile("s_waitcnt vmcnt(0)" ::: "memory");
;             const unsigned og = xb_add(&bar[XB_TOP], 1u);
;             const unsigned tg = og / nx;
;             if (og + 1u == (tg + 1u) * nx) xb_add(&bar[XB_TOPGEN], 1u);
;             else XB_SPIN(xb_ld(&bar[XB_TOPGEN]) == tg, bar);
;             __builtin_amdgcn_fence(__ATOMIC_ACQUIRE, "agent");
;             xb_add(&bar[XB_XGEN(bx)], 1u);
;             asm volatile("s_waitcnt vmcnt(0)" ::: "memory");
;         } else {
;             XB_SPIN(xb_ld(&bar[XB_XGEN(bx)]) == gen, bar);
;             __builtin_amdgcn_fence(__ATOMIC_ACQUIRE, "agent");
;             asm volatile("s_waitcnt vmcnt(0)" ::: "memory");
;         }
;     }
;     __syncthreads();
.LBB0_514:
	s_mov_b64 s[68:69], 0x80000
	s_or_b64 exec, exec, s[4:5]
	s_cmp_eq_u32 s100, 1
	s_cbranch_scc0 .Lp2_514c
	s_mov_b32 s100, 2
	s_mov_b64 s[22:23], exec
	v_readlane_b32 s10, v253, 5
	v_readlane_b32 s11, v253, 6
	s_nop 0
	s_and_b64 s[10:11], s[22:23], s[10:11]
	s_mov_b64 exec, s[10:11]
	s_cbranch_execz .Lp2_wdone
	v_mov_b32_e32 v0, 0x20fa0
	ds_read_b64 v[2:3], v0
	v_readlane_b32 s10, v253, 2
	v_readlane_b32 s11, v253, 3
	s_add_u32 s10, s10, 0x3b00
	s_addc_u32 s11, s11, 0
	v_mov_b64_e32 v[4:5], s[10:11]
	s_waitcnt lgkmcnt(0)
	v_readfirstlane_b32 s14, v3
	s_mul_i32 s14, s14, s98
	s_mov_b32 s16, 0

; __device__ __forceinline__ unsigned xb_ld(unsigned* p)              { return __hip_atomic_load(p, __ATOMIC_RELAXED, __HIP_MEMORY_SCOPE_AGENT); }
; __device__ __forceinline__ unsigned xb_add(unsigned* p, unsigned v) { return __hip_atomic_fetch_add(p, v, __ATOMIC_RELAXED, __HIP_MEMORY_SCOPE_AGENT); }
; #define XB_SPIN(cond, bar) do { unsigned _sp = 0; while (cond) { __builtin_amdgcn_s_sleep(1); \
;     if ((++_sp & 255u) == 0u) { if (xb_ld(&(bar)[XB_TMO])) break; if (_sp > XB_SPIN_CAP) { atomicAdd(&(bar)[XB_TMO], 1u); break; } } } } while (0)
; __device__ __forceinline__ void xcd_barrier(const XcdBarrier& b) {
;     asm volatile("s_waitcnt vmcnt(0)" ::: "memory");
;     __syncthreads();
;     if (threadIdx.x == 0) {
;         unsigned long long bar_ = (unsigned long long)b.bar; unsigned bx = b.x;
;         asm volatile("" : "+s"(bar_), "+s"(bx));
;         unsigned* bar = (unsigned*)bar_;
;         __builtin_amdgcn_s_waitcnt(0);
;         unsigned nloc = b.st[0], nx = b.st[1];
;         if (nloc == 0u) { xcd_barrier_complete(bar, bx, nloc, nx); b.st[0] = nloc; b.st[1] = nx; }
;         const unsigned old = xb_add(&bar[XB_XSUB(bx)], 1u);
;         const unsigned gen = old / nloc;
;         if (old + 1u == (gen + 1u) * nloc) {
;             __builtin_amdgcn_fence(__ATOMIC_RELEASE, "agent");
;             asm volatile("s_waitcnt vmcnt(0)" ::: "memory");
;             const unsigned og = xb_add(&bar[XB_TOP], 1u);
;             const unsigned tg = og / nx;
;             if (og + 1u == (tg + 1u) * nx) xb_add(&bar[XB_TOPGEN], 1u);
;             else XB_SPIN(xb_ld(&bar[XB_TOPGEN]) == tg, bar);
;             __builtin_amdgcn_fence(__ATOMIC_ACQUIRE, "agent");
;             xb_add(&bar[XB_XGEN(bx)], 1u);
;             asm volatile("s_waitcnt vmcnt(0)" ::: "memory");
;         } else {
;             XB_SPIN(xb_ld(&bar[XB_XGEN(bx)]) == gen, bar);
;             __builtin_amdgcn_fence(__ATOMIC_ACQUIRE, "agent");
;             asm volatile("s_waitcnt vmcnt(0)" ::: "memory");
;         }
;     }
;     __syncthreads();
.Lp2_wdone:
	s_mov_b64 exec, s[22:23]
	s_waitcnt lgkmcnt(0)
	s_barrier
	v_mov_b32_e32 v48, v246
	v_readlane_b32 s0, v253, 0
	v_readlane_b32 s1, v253, 1
	s_nop 3
	s_branch .Lp2_hd
.Lp2_514c:
	s_waitcnt vmcnt(0)
	s_waitcnt lgkmcnt(0)
	s_barrier
	s_mov_b64 s[6:7], exec
	v_readlane_b32 s2, v253, 5
	v_readlane_b32 s3, v253, 6
	s_and_b64 s[2:3], s[6:7], s[2:3]
	s_mov_b64 exec, s[2:3]
	s_cbranch_execz .LBB0_558
	s_add_i32 s98, s98, 1
	v_mov_b32_e32 v0, 0x20fa0
	ds_read_b64 v[2:3], v0
	v_readlane_b32 s10, v253, 2
	v_readlane_b32 s11, v253, 3
	v_readlane_b32 s12, v253, 4
	s_lshl_b32 s12, s12, 6
	s_add_i32 s12, s12, 0x3600
	s_add_u32 s14, s10, s12
	s_addc_u32 s15, s11, 0
	s_add_u32 s10, s10, 0x3b00
	s_addc_u32 s11, s11, 0
	v_mov_b64_e32 v[4:5], s[14:15]
	v_mov_b32_e32 v8, 1
	flat_atomic_add v6, v[4:5], v8 sc0
	s_waitcnt vmcnt(0) lgkmcnt(0)
	v_readfirstlane_b32 s12, v6
	v_readfirstlane_b32 s13, v2
	v_readfirstlane_b32 s14, v3
	s_mul_i32 s13, s13, s98
	s_mul_i32 s14, s14, s98
	s_add_i32 s12, s12, 1
	v_mov_b64_e32 v[4:5], s[10:11]
	s_cmp_lg_u32 s12, s13
	s_cbranch_scc1 .Lgb_poll_3
	buffer_wbl2 sc1
	s_waitcnt vmcnt(0) lgkmcnt(0)
	flat_atomic_add v7, v[4:5], v8 sc0
	s_waitcnt vmcnt(0) lgkmcnt(0)
